# FA softmax trimming (MLA/MOBA/WIN): removed canonicalising v_max, conversions fill the pads between dependent pk_adds, l written directly; MLA tile write with immediate LDS offsets
# baseline (speedup 1.0000x reference)
; __device__ __forceinline__ float max3f(float a, float b, float c) { return __builtin_fmaxf(__builtin_fmaxf(a, b), c); }
; __device__ __forceinline__ void partialSM(f32x16& p0, f32x16& p1, float& m_reg, float& mn, float& alpha, const float sc, const float C2) {
;     float pmax = max3f(p0[0], p0[1], p0[2]);
; #pragma unroll
;     for (int r = 3; r < 15; r += 2) pmax = max3f(pmax, p0[r], p0[r + 1]);
;     pmax = max3f(pmax, p0[15], p1[0]);
; #pragma unroll
;     for (int r = 1; r < 15; r += 2) pmax = max3f(pmax, p1[r], p1[r + 1]);
;     pmax = fmaxf(pmax, p1[15]);
;     { auto rr = __builtin_amdgcn_permlane32_swap(__float_as_uint(pmax), __float_as_uint(pmax), false, false);
;       pmax = fmaxf(__uint_as_float(rr[0]), __uint_as_float(rr[1])); }
;     if (__builtin_expect(__all((pmax - m_reg) * sc <= 8.0f), 1)) { mn = m_reg; alpha = 1.f; }
;     else { mn = fmaxf(m_reg, pmax); alpha = __builtin_amdgcn_exp2f((m_reg - mn) * C2); m_reg = mn; }
.LBB0_4957:
	v_max_f32_e32 v4, v98, v99
	v_max3_f32 v4, v4, v100, v101
	v_max3_f32 v4, v4, v102, v103
	v_max3_f32 v4, v4, v104, v105
	v_max3_f32 v4, v4, v106, v107
	v_max3_f32 v4, v4, v108, v109
	v_max3_f32 v4, v4, v110, v111
	v_max3_f32 v4, v4, v112, v113
	v_max3_f32 v4, v4, v82, v83
	v_max3_f32 v4, v4, v84, v85
	v_max3_f32 v4, v4, v86, v87
	v_max3_f32 v4, v4, v88, v89
	v_max3_f32 v4, v4, v90, v91
	v_max3_f32 v4, v4, v92, v93
	v_max3_f32 v4, v4, v94, v95
	v_max3_f32 v4, v4, v96, v97
	v_mov_b32_e32 v5, v4
	s_nop 1
	v_permlane32_swap_b32_e32 v4, v5
	v_max_f32_e32 v4, v4, v5
	v_sub_f32_e32 v5, v4, v236
	v_mul_f32_e32 v5, 0x3db504f3, v5
	v_cmp_ge_f32_e32 vcc, s87, v5
	v_max_f32_e32 v5, v236, v4
	v_sub_f32_e32 v4, v236, v5
	v_mul_f32_e32 v4, 0x3e0293ee, v4
	v_exp_f32_e32 v4, v4
	s_cmp_eq_u64 vcc, exec
	s_cselect_b64 s[38:39], -1, 0
	v_cndmask_b32_e64 v4, v4, 1.0, s[38:39]
	v_cmp_gt_f32_e32 vcc, 1.0, v4
	s_cbranch_vccz .LBB0_4961
	s_and_saveexec_b64 s[8:9], s[0:1]
	ds_write_b32 v226, v4 offset:128
	s_or_b64 exec, exec, s[8:9]
	s_waitcnt lgkmcnt(0)
	ds_read_b128 v[6:9], v1 offset:224
	ds_read_b128 v[10:13], v1 offset:192
	ds_read_b128 v[14:17], v1 offset:160
	ds_read_b128 v[114:117], v1 offset:128
	s_waitcnt lgkmcnt(3)
	v_pk_mul_f32 v[80:81], v[80:81], v[8:9]
	s_waitcnt lgkmcnt(2)
	v_pk_mul_f32 v[76:77], v[76:77], v[12:13]
	s_waitcnt lgkmcnt(1)
	v_pk_mul_f32 v[72:73], v[72:73], v[16:17]
	s_waitcnt lgkmcnt(0)
	v_pk_mul_f32 v[68:69], v[68:69], v[116:117]
	v_pk_mul_f32 v[78:79], v[78:79], v[6:7]
	v_pk_mul_f32 v[74:75], v[74:75], v[10:11]
	v_pk_mul_f32 v[70:71], v[70:71], v[14:15]
	v_pk_mul_f32 v[66:67], v[66:67], v[114:115]
	v_pk_mul_f32 v[64:65], v[64:65], v[8:9]
	v_pk_mul_f32 v[60:61], v[60:61], v[12:13]
	v_pk_mul_f32 v[56:57], v[56:57], v[16:17]
	v_pk_mul_f32 v[52:53], v[52:53], v[116:117]
	v_pk_mul_f32 v[62:63], v[62:63], v[6:7]
	v_pk_mul_f32 v[58:59], v[58:59], v[10:11]
	v_pk_mul_f32 v[54:55], v[54:55], v[14:15]
	v_pk_mul_f32 v[50:51], v[50:51], v[114:115]
	v_pk_mul_f32 v[48:49], v[48:49], v[8:9]
	v_pk_mul_f32 v[44:45], v[44:45], v[12:13]
	v_pk_mul_f32 v[40:41], v[40:41], v[16:17]
	v_pk_mul_f32 v[36:37], v[36:37], v[116:117]
	v_pk_mul_f32 v[46:47], v[46:47], v[6:7]
	v_pk_mul_f32 v[42:43], v[42:43], v[10:11]
	v_pk_mul_f32 v[38:39], v[38:39], v[14:15]
	v_pk_mul_f32 v[34:35], v[34:35], v[114:115]
	v_pk_mul_f32 v[32:33], v[32:33], v[8:9]
	v_pk_mul_f32 v[28:29], v[28:29], v[12:13]
	v_pk_mul_f32 v[24:25], v[24:25], v[16:17]
	v_pk_mul_f32 v[20:21], v[20:21], v[116:117]
	v_pk_mul_f32 v[30:31], v[30:31], v[6:7]
	v_pk_mul_f32 v[26:27], v[26:27], v[10:11]
	v_pk_mul_f32 v[22:23], v[22:23], v[14:15]
	v_pk_mul_f32 v[18:19], v[18:19], v[114:115]
; #define FA_SBAR() __builtin_amdgcn_sched_barrier(0)
; #define FA_RD8(S, d0) do { constexpr int b_ = v_rd_off(d0, 0, 0); FA_TRRD(S##l0, b_); FA_TRRD(S##h0, b_ + 2048); FA_TRRD(S##l1, b_ + 4096); FA_TRRD(S##h1, b_ + 6144); FA_TRRD(S##l2, b_ + 8192); FA_TRRD(S##h2, b_ + 10240); FA_TRRD(S##l3, b_ + 12288); FA_TRRD(S##h3, b_ + 14336); } while (0)
; __device__ __forceinline__ void partialSM(f32x16& p0, f32x16& p1, float& m_reg, float& mn, float& alpha, const float sc, const float C2) {
;     ...
; #pragma unroll
;     for (int r = 0; r < 16; ++r) p0[r] = __builtin_amdgcn_exp2f(fmaf(p0[r], C2, mnL));
; #pragma unroll
;     for (int r = 0; r < 16; ++r) p1[r] = __builtin_amdgcn_exp2f(fmaf(p1[r], C2, mnL));
; }
; __device__ __forceinline__ void finishSM(const f32x16& p0, const f32x16& p1, float alpha, float& l_reg, half8& pa0, half8& pa1, half8& pa2, half8& pa3) {
;     f32x2 s2 = {0.f, 0.f};
; #pragma unroll
;     for (int r = 0; r < 16; r += 2) { s2 += (f32x2){p0[r], p0[r + 1]}; s2 += (f32x2){p1[r], p1[r + 1]}; }
;     float ps = s2[0] + s2[1];
;     { auto rr = __builtin_amdgcn_permlane32_swap(__float_as_uint(ps), __float_as_uint(ps), false, false);
;       ps = __uint_as_float(rr[0]) + __uint_as_float(rr[1]); }
;     l_reg = l_reg * alpha + ps;
;     ...
;     FA_PK4(p0, 0, pa0); FA_PK4(p0, 8, pa1); FA_PK4(p1, 0, pa2); FA_PK4(p1, 8, pa3);
;     ...
; }
; __device__ __forceinline__ void pv_tile2(f32x16* o, int vb0, half8 pa0, half8 pa1, half8 pa2, half8 pa3) {
;     ...
;     s16x4 al0, al1, al2, al3, ah0, ah1, ah2, ah3, bl0, bl1, bl2, bl3, bh0, bh1, bh2, bh3;
;     FA_RD8(a, 0);
;     FA_RD8(b, 1); asm volatile("s_waitcnt lgkmcnt(8)" ::: "memory"); FA_SBAR(); FA_MM4(a, 0); FA_SBAR();
;     FA_RD8(a, 2); asm volatile("s_waitcnt lgkmcnt(8)" ::: "memory"); FA_SBAR(); FA_MM4(b, 1); FA_SBAR();
;     FA_RD8(b, 3); asm volatile("s_waitcnt lgkmcnt(8)" ::: "memory"); FA_SBAR(); FA_MM4(a, 2); FA_SBAR();
;     asm volatile("s_waitcnt lgkmcnt(0)" ::: "memory"); FA_SBAR(); FA_MM4(b, 3);
.LBB0_4961:
	v_cndmask_b32_e64 v236, v5, v236, s[38:39]
	v_mov_b32_e32 v118, v4
	v_mul_f32_e32 v5, 0xbe0293ee, v236
	v_fmamk_f32 v6, v98, 0x3e0293ee, v5
	v_fmamk_f32 v7, v99, 0x3e0293ee, v5
	v_exp_f32_e32 v6, v6
	v_exp_f32_e32 v7, v7
	v_fmamk_f32 v82, v82, 0x3e0293ee, v5
	v_fmamk_f32 v83, v83, 0x3e0293ee, v5
	v_fmamk_f32 v8, v100, 0x3e0293ee, v5
	v_fmamk_f32 v9, v101, 0x3e0293ee, v5
	v_exp_f32_e32 v82, v82
	v_exp_f32_e32 v83, v83
	v_exp_f32_e32 v8, v8
	v_exp_f32_e32 v9, v9
	v_fmamk_f32 v84, v84, 0x3e0293ee, v5
	v_fmamk_f32 v85, v85, 0x3e0293ee, v5
	v_fmamk_f32 v10, v102, 0x3e0293ee, v5
	v_fmamk_f32 v11, v103, 0x3e0293ee, v5
	v_exp_f32_e32 v84, v84
	v_exp_f32_e32 v85, v85
	v_exp_f32_e32 v10, v10
	v_exp_f32_e32 v11, v11
	v_fmamk_f32 v86, v86, 0x3e0293ee, v5
	v_fmamk_f32 v87, v87, 0x3e0293ee, v5
	v_pk_add_f32 v[102:103], v[6:7], 0 op_sel_hi:[1,0]
	v_fmamk_f32 v12, v104, 0x3e0293ee, v5
	v_fmamk_f32 v13, v105, 0x3e0293ee, v5
	v_exp_f32_e32 v86, v86
	v_exp_f32_e32 v87, v87
	v_pk_add_f32 v[102:103], v[82:83], v[102:103]
	v_exp_f32_e32 v12, v12
	v_exp_f32_e32 v13, v13
	v_fmamk_f32 v88, v88, 0x3e0293ee, v5
	v_fmamk_f32 v89, v89, 0x3e0293ee, v5
	v_pk_add_f32 v[102:103], v[8:9], v[102:103]
	v_fmamk_f32 v14, v106, 0x3e0293ee, v5
	v_fmamk_f32 v15, v107, 0x3e0293ee, v5
	v_exp_f32_e32 v88, v88
	v_exp_f32_e32 v89, v89
	v_pk_add_f32 v[102:103], v[84:85], v[102:103]
	v_exp_f32_e32 v14, v14
	v_exp_f32_e32 v15, v15
	v_fmamk_f32 v90, v90, 0x3e0293ee, v5
	v_fmamk_f32 v91, v91, 0x3e0293ee, v5
	v_pk_add_f32 v[102:103], v[10:11], v[102:103]
	v_fmamk_f32 v16, v108, 0x3e0293ee, v5
	v_fmamk_f32 v17, v109, 0x3e0293ee, v5
	v_exp_f32_e32 v90, v90
	v_exp_f32_e32 v91, v91
	v_pk_add_f32 v[102:103], v[86:87], v[102:103]
	v_exp_f32_e32 v16, v16
	v_exp_f32_e32 v17, v17
	v_fmamk_f32 v92, v92, 0x3e0293ee, v5
	v_fmamk_f32 v93, v93, 0x3e0293ee, v5
	v_pk_add_f32 v[102:103], v[12:13], v[102:103]
	v_fmamk_f32 v98, v110, 0x3e0293ee, v5
	v_fmamk_f32 v99, v111, 0x3e0293ee, v5
	v_exp_f32_e32 v92, v92
	v_exp_f32_e32 v93, v93
	v_pk_add_f32 v[102:103], v[88:89], v[102:103]
	v_exp_f32_e32 v98, v98
	v_exp_f32_e32 v99, v99
	v_fmamk_f32 v94, v94, 0x3e0293ee, v5
	v_fmamk_f32 v95, v95, 0x3e0293ee, v5
	v_pk_add_f32 v[102:103], v[14:15], v[102:103]
	v_fmamk_f32 v100, v112, 0x3e0293ee, v5
	v_fmamk_f32 v101, v113, 0x3e0293ee, v5
	v_exp_f32_e32 v94, v94
	v_exp_f32_e32 v95, v95
	v_pk_add_f32 v[102:103], v[90:91], v[102:103]
	v_exp_f32_e32 v100, v100
	v_exp_f32_e32 v101, v101
	v_fmamk_f32 v96, v96, 0x3e0293ee, v5
	v_fmac_f32_e32 v5, 0x3e0293ee, v97
	v_pk_add_f32 v[102:103], v[16:17], v[102:103]
	v_exp_f32_e32 v96, v96
	v_exp_f32_e32 v97, v5
	v_pk_add_f32 v[102:103], v[92:93], v[102:103]
	v_cvt_pk_f16_f32 v4, v6, v7
	v_pk_add_f32 v[102:103], v[98:99], v[102:103]
	v_cvt_pk_f16_f32 v5, v8, v9
	v_pk_add_f32 v[102:103], v[94:95], v[102:103]
	v_cvt_pk_f16_f32 v6, v10, v11
	v_pk_add_f32 v[102:103], v[100:101], v[102:103]
	v_cvt_pk_f16_f32 v7, v12, v13
	v_pk_add_f32 v[102:103], v[96:97], v[102:103]
	v_cvt_pk_f16_f32 v8, v14, v15
	v_pk_add_f32 v[102:103], v[102:103], v[102:103] op_sel:[0,1] op_sel_hi:[1,0]
	v_cvt_pk_f16_f32 v9, v16, v17
	v_mov_b32_e32 v103, v102
	v_cvt_pk_f16_f32 v10, v98, v99
	v_cvt_pk_f16_f32 v11, v100, v101
	v_permlane32_swap_b32_e32 v102, v103
	v_cvt_pk_f16_f32 v12, v82, v83
	v_add_f32_e32 v103, v102, v103
	v_cvt_pk_f16_f32 v13, v84, v85
	v_fma_f32 v237, v237, v118, v103
	v_cvt_pk_f16_f32 v14, v86, v87
	v_cvt_pk_f16_f32 v15, v88, v89
	v_cvt_pk_f16_f32 v82, v90, v91
	v_cvt_pk_f16_f32 v83, v92, v93
	v_cvt_pk_f16_f32 v84, v94, v95
	v_cvt_pk_f16_f32 v85, v96, v97
	v_permlane32_swap_b32_e32 v4, v6
	v_permlane32_swap_b32_e32 v5, v7
	v_permlane32_swap_b32_e32 v8, v10
	v_permlane32_swap_b32_e32 v9, v11
	v_permlane32_swap_b32_e32 v12, v14
	v_permlane32_swap_b32_e32 v13, v15
	v_permlane32_swap_b32_e32 v82, v84
	v_permlane32_swap_b32_e32 v83, v85
	v_add_u32_e32 v2, v234, v2
	ds_read_b64_tr_b16 v[86:87], v2 offset:0
	ds_read_b64_tr_b16 v[88:89], v2 offset:0x800
	ds_read_b64_tr_b16 v[90:91], v2 offset:0x1000
	ds_read_b64_tr_b16 v[92:93], v2 offset:0x1800
	ds_read_b64_tr_b16 v[94:95], v2 offset:0x2000
	ds_read_b64_tr_b16 v[96:97], v2 offset:0x2800
	ds_read_b64_tr_b16 v[98:99], v2 offset:0x3000
	ds_read_b64_tr_b16 v[100:101], v2 offset:0x3800
	ds_read_b64_tr_b16 v[102:103], v2 offset:0x200
	ds_read_b64_tr_b16 v[104:105], v2 offset:0xa00
	ds_read_b64_tr_b16 v[106:107], v2 offset:0x1200
	ds_read_b64_tr_b16 v[108:109], v2 offset:0x1a00
	ds_read_b64_tr_b16 v[110:111], v2 offset:0x2200
	ds_read_b64_tr_b16 v[112:113], v2 offset:0x2a00
	ds_read_b64_tr_b16 v[114:115], v2 offset:0x3200
	ds_read_b64_tr_b16 v[116:117], v2 offset:0x3a00
	s_waitcnt lgkmcnt(8)
	s_nop 0
	v_mfma_f32_32x32x16_f16 v[66:81], v[4:7], v[86:89], v[66:81]
	v_mfma_f32_32x32x16_f16 v[66:81], v[8:11], v[90:93], v[66:81]
	v_mfma_f32_32x32x16_f16 v[66:81], v[12:15], v[94:97], v[66:81]
	v_mfma_f32_32x32x16_f16 v[66:81], v[82:85], v[98:101], v[66:81]
	ds_read_b64_tr_b16 v[86:87], v2 offset:0x400
	ds_read_b64_tr_b16 v[88:89], v2 offset:0xc00
	ds_read_b64_tr_b16 v[90:91], v2 offset:0x1400
	ds_read_b64_tr_b16 v[92:93], v2 offset:0x1c00
	ds_read_b64_tr_b16 v[94:95], v2 offset:0x2400
	ds_read_b64_tr_b16 v[96:97], v2 offset:0x2c00
	ds_read_b64_tr_b16 v[98:99], v2 offset:0x3400
	ds_read_b64_tr_b16 v[100:101], v2 offset:0x3c00
	s_waitcnt lgkmcnt(8)
	v_mfma_f32_32x32x16_f16 v[50:65], v[4:7], v[102:105], v[50:65]
	v_mfma_f32_32x32x16_f16 v[50:65], v[8:11], v[106:109], v[50:65]
	v_mfma_f32_32x32x16_f16 v[50:65], v[12:15], v[110:113], v[50:65]
	v_mfma_f32_32x32x16_f16 v[50:65], v[82:85], v[114:117], v[50:65]
	ds_read_b64_tr_b16 v[102:103], v2 offset:0x600
	ds_read_b64_tr_b16 v[104:105], v2 offset:0xe00
	ds_read_b64_tr_b16 v[106:107], v2 offset:0x1600
	ds_read_b64_tr_b16 v[108:109], v2 offset:0x1e00
	ds_read_b64_tr_b16 v[110:111], v2 offset:0x2600
	ds_read_b64_tr_b16 v[112:113], v2 offset:0x2e00
	ds_read_b64_tr_b16 v[114:115], v2 offset:0x3600
	ds_read_b64_tr_b16 v[116:117], v2 offset:0x3e00
	s_waitcnt lgkmcnt(8)
	v_mfma_f32_32x32x16_f16 v[34:49], v[4:7], v[86:89], v[34:49]
	v_mfma_f32_32x32x16_f16 v[34:49], v[8:11], v[90:93], v[34:49]
	v_mfma_f32_32x32x16_f16 v[34:49], v[12:15], v[94:97], v[34:49]
	v_mfma_f32_32x32x16_f16 v[34:49], v[82:85], v[98:101], v[34:49]
	s_waitcnt lgkmcnt(0)
	v_mfma_f32_32x32x16_f16 v[18:33], v[4:7], v[102:105], v[18:33]
	v_mfma_f32_32x32x16_f16 v[18:33], v[8:11], v[106:109], v[18:33]
	v_mfma_f32_32x32x16_f16 v[18:33], v[12:15], v[110:113], v[18:33]
	v_mfma_f32_32x32x16_f16 v[18:33], v[82:85], v[114:117], v[18:33]

; __device__ __forceinline__ float max3f(float a, float b, float c) { return __builtin_fmaxf(__builtin_fmaxf(a, b), c); }
; __device__ __forceinline__ void partialSM(f32x16& p0, f32x16& p1, float& m_reg, float& mn, float& alpha, const float sc, const float C2) {
;     float pmax = max3f(p0[0], p0[1], p0[2]);
; #pragma unroll
;     for (int r = 3; r < 15; r += 2) pmax = max3f(pmax, p0[r], p0[r + 1]);
;     pmax = max3f(pmax, p0[15], p1[0]);
; #pragma unroll
;     for (int r = 1; r < 15; r += 2) pmax = max3f(pmax, p1[r], p1[r + 1]);
;     pmax = fmaxf(pmax, p1[15]);
;     { auto rr = __builtin_amdgcn_permlane32_swap(__float_as_uint(pmax), __float_as_uint(pmax), false, false);
;       pmax = fmaxf(__uint_as_float(rr[0]), __uint_as_float(rr[1])); }
;     if (__builtin_expect(__all((pmax - m_reg) * sc <= 8.0f), 1)) { mn = m_reg; alpha = 1.f; }
;     else { mn = fmaxf(m_reg, pmax); alpha = __builtin_amdgcn_exp2f((m_reg - mn) * C2); m_reg = mn; }
.LBB0_4977:
	s_nop 8
	v_max_f32_e32 v4, v98, v99
	v_max3_f32 v4, v4, v100, v101
	v_max3_f32 v4, v4, v102, v103
	v_max3_f32 v4, v4, v104, v105
	v_max3_f32 v4, v4, v106, v107
	v_max3_f32 v4, v4, v108, v109
	v_max3_f32 v4, v4, v110, v111
	v_max3_f32 v4, v4, v112, v113
	v_max3_f32 v4, v4, v82, v83
	v_max3_f32 v4, v4, v84, v85
	v_max3_f32 v4, v4, v86, v87
	v_max3_f32 v4, v4, v88, v89
	v_max3_f32 v4, v4, v90, v91
	v_max3_f32 v4, v4, v92, v93
	v_max3_f32 v4, v4, v94, v95
	v_max3_f32 v4, v4, v96, v97
	v_mov_b32_e32 v5, v4
	s_nop 1
	v_permlane32_swap_b32_e32 v4, v5
	v_max_f32_e32 v4, v4, v5
	v_sub_f32_e32 v5, v4, v228
	v_mul_f32_e32 v5, 0x3d93cd3a, v5
	v_cmp_ge_f32_e32 vcc, s87, v5
	v_max_f32_e32 v5, v228, v4
	v_sub_f32_e32 v4, v228, v5
	v_mul_f32_e32 v4, 0x3dd53b94, v4
	v_exp_f32_e32 v4, v4
	s_cmp_eq_u64 vcc, exec
	s_cselect_b64 s[38:39], -1, 0
	v_cndmask_b32_e64 v4, v4, 1.0, s[38:39]
	v_cmp_gt_f32_e32 vcc, 1.0, v4
	s_cbranch_vccz .LBB0_4981
	s_and_saveexec_b64 s[8:9], s[0:1]
	ds_write_b32 v206, v4 offset:128
	s_or_b64 exec, exec, s[8:9]
	s_waitcnt lgkmcnt(0)
	ds_read_b128 v[6:9], v1 offset:224
	ds_read_b128 v[10:13], v1 offset:192
	ds_read_b128 v[14:17], v1 offset:160
	ds_read_b128 v[194:197], v1 offset:128
	s_waitcnt lgkmcnt(3)
	v_pk_mul_f32 v[80:81], v[80:81], v[8:9]
	s_waitcnt lgkmcnt(2)
	v_pk_mul_f32 v[76:77], v[76:77], v[12:13]
	s_waitcnt lgkmcnt(1)
	v_pk_mul_f32 v[72:73], v[72:73], v[16:17]
	s_waitcnt lgkmcnt(0)
	v_pk_mul_f32 v[68:69], v[68:69], v[196:197]
	v_pk_mul_f32 v[78:79], v[78:79], v[6:7]
	v_pk_mul_f32 v[74:75], v[74:75], v[10:11]
	v_pk_mul_f32 v[70:71], v[70:71], v[14:15]
	v_pk_mul_f32 v[66:67], v[66:67], v[194:195]
	v_pk_mul_f32 v[64:65], v[64:65], v[8:9]
	v_pk_mul_f32 v[60:61], v[60:61], v[12:13]
	v_pk_mul_f32 v[56:57], v[56:57], v[16:17]
	v_pk_mul_f32 v[52:53], v[52:53], v[196:197]
	v_pk_mul_f32 v[62:63], v[62:63], v[6:7]
	v_pk_mul_f32 v[58:59], v[58:59], v[10:11]
	v_pk_mul_f32 v[54:55], v[54:55], v[14:15]
	v_pk_mul_f32 v[50:51], v[50:51], v[194:195]
	v_pk_mul_f32 v[48:49], v[48:49], v[8:9]
	v_pk_mul_f32 v[44:45], v[44:45], v[12:13]
	v_pk_mul_f32 v[40:41], v[40:41], v[16:17]
	v_pk_mul_f32 v[36:37], v[36:37], v[196:197]
	v_pk_mul_f32 v[46:47], v[46:47], v[6:7]
	v_pk_mul_f32 v[42:43], v[42:43], v[10:11]
	v_pk_mul_f32 v[38:39], v[38:39], v[14:15]
	v_pk_mul_f32 v[34:35], v[34:35], v[194:195]
	v_pk_mul_f32 v[32:33], v[32:33], v[8:9]
	v_pk_mul_f32 v[28:29], v[28:29], v[12:13]
	v_pk_mul_f32 v[24:25], v[24:25], v[16:17]
	v_pk_mul_f32 v[20:21], v[20:21], v[196:197]
	v_pk_mul_f32 v[30:31], v[30:31], v[6:7]
	v_pk_mul_f32 v[26:27], v[26:27], v[10:11]
	v_pk_mul_f32 v[22:23], v[22:23], v[14:15]
	v_pk_mul_f32 v[18:19], v[18:19], v[194:195]
.LBB0_4981:
	v_cndmask_b32_e64 v228, v5, v228, s[38:39]
	v_mov_b32_e32 v214, v4
	v_mul_f32_e32 v5, 0xbdd53b94, v228
	v_fmamk_f32 v6, v98, 0x3dd53b94, v5
	v_fmamk_f32 v7, v99, 0x3dd53b94, v5
	v_exp_f32_e32 v6, v6
	v_exp_f32_e32 v7, v7
	v_fmamk_f32 v82, v82, 0x3dd53b94, v5
	v_fmamk_f32 v83, v83, 0x3dd53b94, v5
	v_fmamk_f32 v8, v100, 0x3dd53b94, v5
	v_fmamk_f32 v9, v101, 0x3dd53b94, v5
	v_exp_f32_e32 v82, v82
	v_exp_f32_e32 v83, v83
	v_exp_f32_e32 v8, v8
	v_exp_f32_e32 v9, v9
	v_fmamk_f32 v84, v84, 0x3dd53b94, v5
	v_fmamk_f32 v85, v85, 0x3dd53b94, v5
	v_fmamk_f32 v10, v102, 0x3dd53b94, v5
	v_fmamk_f32 v11, v103, 0x3dd53b94, v5
	v_exp_f32_e32 v84, v84
	v_exp_f32_e32 v85, v85
	v_exp_f32_e32 v10, v10
	v_exp_f32_e32 v11, v11
	v_fmamk_f32 v86, v86, 0x3dd53b94, v5
	v_fmamk_f32 v87, v87, 0x3dd53b94, v5
	v_pk_add_f32 v[102:103], v[6:7], 0 op_sel_hi:[1,0]
	v_fmamk_f32 v12, v104, 0x3dd53b94, v5
	v_fmamk_f32 v13, v105, 0x3dd53b94, v5
	v_exp_f32_e32 v86, v86
	v_exp_f32_e32 v87, v87
	v_pk_add_f32 v[102:103], v[82:83], v[102:103]
	v_exp_f32_e32 v12, v12
	v_exp_f32_e32 v13, v13
	v_fmamk_f32 v88, v88, 0x3dd53b94, v5
	v_fmamk_f32 v89, v89, 0x3dd53b94, v5
	v_pk_add_f32 v[102:103], v[8:9], v[102:103]
	v_fmamk_f32 v14, v106, 0x3dd53b94, v5
	v_fmamk_f32 v15, v107, 0x3dd53b94, v5
	v_exp_f32_e32 v88, v88
	v_exp_f32_e32 v89, v89
	v_pk_add_f32 v[102:103], v[84:85], v[102:103]
	v_exp_f32_e32 v14, v14
	v_exp_f32_e32 v15, v15
	v_fmamk_f32 v90, v90, 0x3dd53b94, v5
	v_fmamk_f32 v91, v91, 0x3dd53b94, v5
	v_pk_add_f32 v[102:103], v[10:11], v[102:103]
	v_fmamk_f32 v16, v108, 0x3dd53b94, v5
	v_fmamk_f32 v17, v109, 0x3dd53b94, v5
	v_exp_f32_e32 v90, v90
	v_exp_f32_e32 v91, v91
	v_pk_add_f32 v[102:103], v[86:87], v[102:103]
	v_exp_f32_e32 v16, v16
	v_exp_f32_e32 v17, v17
	v_fmamk_f32 v92, v92, 0x3dd53b94, v5
	v_fmamk_f32 v93, v93, 0x3dd53b94, v5
	v_pk_add_f32 v[102:103], v[12:13], v[102:103]
	v_fmamk_f32 v98, v110, 0x3dd53b94, v5
	v_fmamk_f32 v99, v111, 0x3dd53b94, v5
	v_exp_f32_e32 v92, v92
	v_exp_f32_e32 v93, v93
	v_pk_add_f32 v[102:103], v[88:89], v[102:103]
	v_exp_f32_e32 v98, v98
	v_exp_f32_e32 v99, v99
	v_fmamk_f32 v94, v94, 0x3dd53b94, v5
	v_fmamk_f32 v95, v95, 0x3dd53b94, v5
	v_pk_add_f32 v[102:103], v[14:15], v[102:103]
; #define FA_SBAR() __builtin_amdgcn_sched_barrier(0)
; #define FA_RD8(S, d0) do { constexpr int b_ = v_rd_off(d0, 0, 0); FA_TRRD(S##l0, b_); FA_TRRD(S##h0, b_ + 2048); FA_TRRD(S##l1, b_ + 4096); FA_TRRD(S##h1, b_ + 6144); FA_TRRD(S##l2, b_ + 8192); FA_TRRD(S##h2, b_ + 10240); FA_TRRD(S##l3, b_ + 12288); FA_TRRD(S##h3, b_ + 14336); } while (0)
; __device__ __forceinline__ void finishSM(const f32x16& p0, const f32x16& p1, float alpha, float& l_reg, half8& pa0, half8& pa1, half8& pa2, half8& pa3) {
;     f32x2 s2 = {0.f, 0.f};
; #pragma unroll
;     for (int r = 0; r < 16; r += 2) { s2 += (f32x2){p0[r], p0[r + 1]}; s2 += (f32x2){p1[r], p1[r + 1]}; }
;     float ps = s2[0] + s2[1];
;     { auto rr = __builtin_amdgcn_permlane32_swap(__float_as_uint(ps), __float_as_uint(ps), false, false);
;       ps = __uint_as_float(rr[0]) + __uint_as_float(rr[1]); }
;     l_reg = l_reg * alpha + ps;
;     ...
;     FA_PK4(p0, 0, pa0); FA_PK4(p0, 8, pa1); FA_PK4(p1, 0, pa2); FA_PK4(p1, 8, pa3);
;     ...
; }
; __device__ __forceinline__ void pv_tile2(f32x16* o, int vb0, half8 pa0, half8 pa1, half8 pa2, half8 pa3) {
;     ...
;     s16x4 al0, al1, al2, al3, ah0, ah1, ah2, ah3, bl0, bl1, bl2, bl3, bh0, bh1, bh2, bh3;
;     FA_RD8(a, 0);
;     FA_RD8(b, 1); asm volatile("s_waitcnt lgkmcnt(8)" ::: "memory"); FA_SBAR(); FA_MM4(a, 0); FA_SBAR();
;     FA_RD8(a, 2); asm volatile("s_waitcnt lgkmcnt(8)" ::: "memory"); FA_SBAR(); FA_MM4(b, 1); FA_SBAR();
;     FA_RD8(b, 3); asm volatile("s_waitcnt lgkmcnt(8)" ::: "memory"); FA_SBAR(); FA_MM4(a, 2); FA_SBAR();
;     asm volatile("s_waitcnt lgkmcnt(0)" ::: "memory"); FA_SBAR(); FA_MM4(b, 3);
	v_fmamk_f32 v100, v112, 0x3dd53b94, v5
	v_fmamk_f32 v101, v113, 0x3dd53b94, v5
	v_exp_f32_e32 v94, v94
	v_exp_f32_e32 v95, v95
	v_pk_add_f32 v[102:103], v[90:91], v[102:103]
	v_exp_f32_e32 v100, v100
	v_exp_f32_e32 v101, v101
	v_fmamk_f32 v96, v96, 0x3dd53b94, v5
	v_fmac_f32_e32 v5, 0x3dd53b94, v97
	v_pk_add_f32 v[102:103], v[16:17], v[102:103]
	v_exp_f32_e32 v96, v96
	v_exp_f32_e32 v97, v5
	v_pk_add_f32 v[102:103], v[92:93], v[102:103]
	v_cvt_pk_f16_f32 v4, v6, v7
	v_pk_add_f32 v[102:103], v[98:99], v[102:103]
	v_cvt_pk_f16_f32 v5, v8, v9
	v_pk_add_f32 v[102:103], v[94:95], v[102:103]
	v_cvt_pk_f16_f32 v6, v10, v11
	v_pk_add_f32 v[102:103], v[100:101], v[102:103]
	v_cvt_pk_f16_f32 v7, v12, v13
	v_pk_add_f32 v[102:103], v[96:97], v[102:103]
	v_cvt_pk_f16_f32 v8, v14, v15
	v_pk_add_f32 v[102:103], v[102:103], v[102:103] op_sel:[0,1] op_sel_hi:[1,0]
	v_cvt_pk_f16_f32 v9, v16, v17
	v_mov_b32_e32 v103, v102
	v_cvt_pk_f16_f32 v10, v98, v99
	v_cvt_pk_f16_f32 v11, v100, v101
	v_permlane32_swap_b32_e32 v102, v103
	v_cvt_pk_f16_f32 v12, v82, v83
	v_add_f32_e32 v103, v102, v103
	v_cvt_pk_f16_f32 v13, v84, v85
	v_fma_f32 v229, v229, v214, v103
	v_cvt_pk_f16_f32 v14, v86, v87
	v_cvt_pk_f16_f32 v15, v88, v89
	v_cvt_pk_f16_f32 v82, v90, v91
	v_cvt_pk_f16_f32 v83, v92, v93
	v_cvt_pk_f16_f32 v84, v94, v95
	v_cvt_pk_f16_f32 v85, v96, v97
	v_permlane32_swap_b32_e32 v4, v6
	v_permlane32_swap_b32_e32 v5, v7
	v_permlane32_swap_b32_e32 v8, v10
	v_permlane32_swap_b32_e32 v9, v11
	v_permlane32_swap_b32_e32 v12, v14
	v_permlane32_swap_b32_e32 v13, v15
	v_permlane32_swap_b32_e32 v82, v84
	v_permlane32_swap_b32_e32 v83, v85
	v_add_u32_e32 v2, v225, v2
	ds_read_b64_tr_b16 v[86:87], v2 offset:0
	ds_read_b64_tr_b16 v[88:89], v2 offset:0x800
	ds_read_b64_tr_b16 v[90:91], v2 offset:0x1000
	ds_read_b64_tr_b16 v[92:93], v2 offset:0x1800
	ds_read_b64_tr_b16 v[94:95], v2 offset:0x2000
	ds_read_b64_tr_b16 v[96:97], v2 offset:0x2800
	ds_read_b64_tr_b16 v[98:99], v2 offset:0x3000
	ds_read_b64_tr_b16 v[100:101], v2 offset:0x3800
	ds_read_b64_tr_b16 v[102:103], v2 offset:0x200
	ds_read_b64_tr_b16 v[104:105], v2 offset:0xa00
	ds_read_b64_tr_b16 v[106:107], v2 offset:0x1200
	ds_read_b64_tr_b16 v[108:109], v2 offset:0x1a00
	ds_read_b64_tr_b16 v[110:111], v2 offset:0x2200
	ds_read_b64_tr_b16 v[112:113], v2 offset:0x2a00
	ds_read_b64_tr_b16 v[194:195], v2 offset:0x3200
	ds_read_b64_tr_b16 v[196:197], v2 offset:0x3a00
	s_waitcnt lgkmcnt(8)
	s_nop 0
	v_mfma_f32_32x32x16_f16 v[66:81], v[4:7], v[86:89], v[66:81]
	v_mfma_f32_32x32x16_f16 v[66:81], v[8:11], v[90:93], v[66:81]
	v_mfma_f32_32x32x16_f16 v[66:81], v[12:15], v[94:97], v[66:81]
	v_mfma_f32_32x32x16_f16 v[66:81], v[82:85], v[98:101], v[66:81]
	ds_read_b64_tr_b16 v[86:87], v2 offset:0x400
	ds_read_b64_tr_b16 v[88:89], v2 offset:0xc00
	ds_read_b64_tr_b16 v[90:91], v2 offset:0x1400
	ds_read_b64_tr_b16 v[92:93], v2 offset:0x1c00
	ds_read_b64_tr_b16 v[94:95], v2 offset:0x2400
	ds_read_b64_tr_b16 v[96:97], v2 offset:0x2c00
	ds_read_b64_tr_b16 v[98:99], v2 offset:0x3400
	ds_read_b64_tr_b16 v[100:101], v2 offset:0x3c00
	s_waitcnt lgkmcnt(8)
	v_mfma_f32_32x32x16_f16 v[50:65], v[4:7], v[102:105], v[50:65]
	v_mfma_f32_32x32x16_f16 v[50:65], v[8:11], v[106:109], v[50:65]
	v_mfma_f32_32x32x16_f16 v[50:65], v[12:15], v[110:113], v[50:65]
	v_mfma_f32_32x32x16_f16 v[50:65], v[82:85], v[194:197], v[50:65]
	ds_read_b64_tr_b16 v[102:103], v2 offset:0x600
	ds_read_b64_tr_b16 v[104:105], v2 offset:0xe00
	ds_read_b64_tr_b16 v[106:107], v2 offset:0x1600
	ds_read_b64_tr_b16 v[108:109], v2 offset:0x1e00
	ds_read_b64_tr_b16 v[110:111], v2 offset:0x2600
	ds_read_b64_tr_b16 v[112:113], v2 offset:0x2e00
	ds_read_b64_tr_b16 v[194:195], v2 offset:0x3600
	ds_read_b64_tr_b16 v[196:197], v2 offset:0x3e00
	s_waitcnt lgkmcnt(8)
	v_mfma_f32_32x32x16_f16 v[34:49], v[4:7], v[86:89], v[34:49]
	v_mfma_f32_32x32x16_f16 v[34:49], v[8:11], v[90:93], v[34:49]
	v_mfma_f32_32x32x16_f16 v[34:49], v[12:15], v[94:97], v[34:49]
	v_mfma_f32_32x32x16_f16 v[34:49], v[82:85], v[98:101], v[34:49]
	s_waitcnt lgkmcnt(0)
	v_mfma_f32_32x32x16_f16 v[18:33], v[4:7], v[102:105], v[18:33]
	v_mfma_f32_32x32x16_f16 v[18:33], v[8:11], v[106:109], v[18:33]
	v_mfma_f32_32x32x16_f16 v[18:33], v[12:15], v[110:113], v[18:33]
	v_mfma_f32_32x32x16_f16 v[18:33], v[82:85], v[194:197], v[18:33]
.LBB0_4982:
	s_add_i32 s23, s23, 1
	s_andn2_b64 vcc, exec, s[6:7]
	s_cbranch_vccnz .LBB0_4971
	s_bitcmp1_b32 s23, 0
	s_waitcnt vmcnt(0)
	s_cbranch_scc1 .Lmla_w1
	ds_write_b128 v207, v[114:117] offset:32768
	ds_write_b128 v207, v[118:121] offset:40960
	ds_write_b128 v204, v[122:125]
	ds_write_b128 v205, v[126:129]
	ds_write_b128 v208, v[178:181]
	s_branch .LBB0_4971
.Lmla_w1:
	ds_write_b128 v207, v[114:117] offset:49152
	ds_write_b128 v207, v[118:121] offset:57344
	ds_write_b128 v204, v[122:125] offset:16384
	ds_write_b128 v205, v[126:129] offset:16384
	ds_write_b128 v208, v[178:181] offset:8192
	s_branch .LBB0_4971

; __device__ __forceinline__ float max3f(float a, float b, float c) { return __builtin_fmaxf(__builtin_fmaxf(a, b), c); }
; __device__ __forceinline__ void partialSM(f32x16& p0, f32x16& p1, float& m_reg, float& mn, float& alpha, const float sc, const float C2) {
;     float pmax = max3f(p0[0], p0[1], p0[2]);
; #pragma unroll
;     for (int r = 3; r < 15; r += 2) pmax = max3f(pmax, p0[r], p0[r + 1]);
;     pmax = max3f(pmax, p0[15], p1[0]);
; #pragma unroll
;     for (int r = 1; r < 15; r += 2) pmax = max3f(pmax, p1[r], p1[r + 1]);
;     pmax = fmaxf(pmax, p1[15]);
;     { auto rr = __builtin_amdgcn_permlane32_swap(__float_as_uint(pmax), __float_as_uint(pmax), false, false);
;       pmax = fmaxf(__uint_as_float(rr[0]), __uint_as_float(rr[1])); }
;     if (__builtin_expect(__all((pmax - m_reg) * sc <= 8.0f), 1)) { mn = m_reg; alpha = 1.f; }
;     else { mn = fmaxf(m_reg, pmax); alpha = __builtin_amdgcn_exp2f((m_reg - mn) * C2); m_reg = mn; }
.LBB0_5011:
	s_nop 8
	v_max_f32_e32 v4, v98, v99
	v_max3_f32 v4, v4, v100, v101
	v_max3_f32 v4, v4, v102, v103
	v_max3_f32 v4, v4, v104, v105
	v_max3_f32 v4, v4, v106, v107
	v_max3_f32 v4, v4, v108, v109
	v_max3_f32 v4, v4, v110, v111
	v_max3_f32 v4, v4, v112, v113
	v_max3_f32 v4, v4, v82, v83
	v_max3_f32 v4, v4, v84, v85
	v_max3_f32 v4, v4, v86, v87
	v_max3_f32 v4, v4, v88, v89
	v_max3_f32 v4, v4, v90, v91
	v_max3_f32 v4, v4, v92, v93
	v_max3_f32 v4, v4, v94, v95
	v_max3_f32 v4, v4, v96, v97
	v_mov_b32_e32 v5, v4
	s_nop 1
	v_permlane32_swap_b32_e32 v4, v5
	v_max_f32_e32 v4, v4, v5
	v_sub_f32_e32 v5, v4, v182
	v_mul_f32_e32 v5, 0x3db504f3, v5
	v_cmp_ge_f32_e32 vcc, s87, v5
	v_max_f32_e32 v5, v182, v4
	v_sub_f32_e32 v4, v182, v5
	v_mul_f32_e32 v4, 0x3e0293ee, v4
	v_exp_f32_e32 v4, v4
	s_cmp_eq_u64 vcc, exec
	s_cselect_b64 s[38:39], -1, 0
	v_cndmask_b32_e64 v4, v4, 1.0, s[38:39]
	v_cmp_gt_f32_e32 vcc, 1.0, v4
	s_cbranch_vccz .LBB0_5015
	s_and_saveexec_b64 s[12:13], s[0:1]
	ds_write_b32 v169, v4 offset:128
	s_or_b64 exec, exec, s[12:13]
	s_waitcnt lgkmcnt(0)
	ds_read_b128 v[6:9], v179 offset:224
	ds_read_b128 v[10:13], v179 offset:192
	ds_read_b128 v[14:17], v179 offset:160
	ds_read_b128 v[184:187], v179 offset:128
	s_waitcnt lgkmcnt(3)
	v_pk_mul_f32 v[80:81], v[80:81], v[8:9]
	s_waitcnt lgkmcnt(2)
	v_pk_mul_f32 v[76:77], v[76:77], v[12:13]
	s_waitcnt lgkmcnt(1)
	v_pk_mul_f32 v[72:73], v[72:73], v[16:17]
	s_waitcnt lgkmcnt(0)
	v_pk_mul_f32 v[68:69], v[68:69], v[186:187]
	v_pk_mul_f32 v[78:79], v[78:79], v[6:7]
	v_pk_mul_f32 v[74:75], v[74:75], v[10:11]
	v_pk_mul_f32 v[70:71], v[70:71], v[14:15]
	v_pk_mul_f32 v[66:67], v[66:67], v[184:185]
	v_pk_mul_f32 v[64:65], v[64:65], v[8:9]
	v_pk_mul_f32 v[60:61], v[60:61], v[12:13]
	v_pk_mul_f32 v[56:57], v[56:57], v[16:17]
	v_pk_mul_f32 v[52:53], v[52:53], v[186:187]
	v_pk_mul_f32 v[62:63], v[62:63], v[6:7]
	v_pk_mul_f32 v[58:59], v[58:59], v[10:11]
	v_pk_mul_f32 v[54:55], v[54:55], v[14:15]
	v_pk_mul_f32 v[50:51], v[50:51], v[184:185]
	v_pk_mul_f32 v[48:49], v[48:49], v[8:9]
	v_pk_mul_f32 v[44:45], v[44:45], v[12:13]
	v_pk_mul_f32 v[40:41], v[40:41], v[16:17]
	v_pk_mul_f32 v[36:37], v[36:37], v[186:187]
	v_pk_mul_f32 v[46:47], v[46:47], v[6:7]
	v_pk_mul_f32 v[42:43], v[42:43], v[10:11]
	v_pk_mul_f32 v[38:39], v[38:39], v[14:15]
	v_pk_mul_f32 v[34:35], v[34:35], v[184:185]
	v_pk_mul_f32 v[32:33], v[32:33], v[8:9]
	v_pk_mul_f32 v[28:29], v[28:29], v[12:13]
	v_pk_mul_f32 v[24:25], v[24:25], v[16:17]
	v_pk_mul_f32 v[20:21], v[20:21], v[186:187]
	v_pk_mul_f32 v[30:31], v[30:31], v[6:7]
	v_pk_mul_f32 v[26:27], v[26:27], v[10:11]
	v_pk_mul_f32 v[22:23], v[22:23], v[14:15]
	v_pk_mul_f32 v[18:19], v[18:19], v[184:185]
; #define FA_SBAR() __builtin_amdgcn_sched_barrier(0)
; #define FA_RD8(S, d0) do { constexpr int b_ = v_rd_off(d0, 0, 0); FA_TRRD(S##l0, b_); FA_TRRD(S##h0, b_ + 2048); FA_TRRD(S##l1, b_ + 4096); FA_TRRD(S##h1, b_ + 6144); FA_TRRD(S##l2, b_ + 8192); FA_TRRD(S##h2, b_ + 10240); FA_TRRD(S##l3, b_ + 12288); FA_TRRD(S##h3, b_ + 14336); } while (0)
; __device__ __forceinline__ void partialSM(f32x16& p0, f32x16& p1, float& m_reg, float& mn, float& alpha, const float sc, const float C2) {
;     ...
; #pragma unroll
;     for (int r = 0; r < 16; ++r) p0[r] = __builtin_amdgcn_exp2f(fmaf(p0[r], C2, mnL));
; #pragma unroll
;     for (int r = 0; r < 16; ++r) p1[r] = __builtin_amdgcn_exp2f(fmaf(p1[r], C2, mnL));
; }
; __device__ __forceinline__ void finishSM(const f32x16& p0, const f32x16& p1, float alpha, float& l_reg, half8& pa0, half8& pa1, half8& pa2, half8& pa3) {
;     f32x2 s2 = {0.f, 0.f};
; #pragma unroll
;     for (int r = 0; r < 16; r += 2) { s2 += (f32x2){p0[r], p0[r + 1]}; s2 += (f32x2){p1[r], p1[r + 1]}; }
;     float ps = s2[0] + s2[1];
;     { auto rr = __builtin_amdgcn_permlane32_swap(__float_as_uint(ps), __float_as_uint(ps), false, false);
;       ps = __uint_as_float(rr[0]) + __uint_as_float(rr[1]); }
;     l_reg = l_reg * alpha + ps;
;     ...
;     FA_PK4(p0, 0, pa0); FA_PK4(p0, 8, pa1); FA_PK4(p1, 0, pa2); FA_PK4(p1, 8, pa3);
;     ...
; }
; __device__ __forceinline__ void pv_tile2(f32x16* o, int vb0, half8 pa0, half8 pa1, half8 pa2, half8 pa3) {
;     ...
;     s16x4 al0, al1, al2, al3, ah0, ah1, ah2, ah3, bl0, bl1, bl2, bl3, bh0, bh1, bh2, bh3;
;     FA_RD8(a, 0);
;     FA_RD8(b, 1); asm volatile("s_waitcnt lgkmcnt(8)" ::: "memory"); FA_SBAR(); FA_MM4(a, 0); FA_SBAR();
;     FA_RD8(a, 2); asm volatile("s_waitcnt lgkmcnt(8)" ::: "memory"); FA_SBAR(); FA_MM4(b, 1); FA_SBAR();
;     FA_RD8(b, 3); asm volatile("s_waitcnt lgkmcnt(8)" ::: "memory"); FA_SBAR(); FA_MM4(a, 2); FA_SBAR();
;     asm volatile("s_waitcnt lgkmcnt(0)" ::: "memory"); FA_SBAR(); FA_MM4(b, 3);
.LBB0_5015:
	v_cndmask_b32_e64 v182, v5, v182, s[38:39]
	v_mov_b32_e32 v188, v4
	v_mul_f32_e32 v5, 0xbe0293ee, v182
	v_fmamk_f32 v6, v98, 0x3e0293ee, v5
	v_fmamk_f32 v7, v99, 0x3e0293ee, v5
	v_exp_f32_e32 v6, v6
	v_exp_f32_e32 v7, v7
	v_fmamk_f32 v82, v82, 0x3e0293ee, v5
	v_fmamk_f32 v83, v83, 0x3e0293ee, v5
	v_fmamk_f32 v8, v100, 0x3e0293ee, v5
	v_fmamk_f32 v9, v101, 0x3e0293ee, v5
	v_exp_f32_e32 v82, v82
	v_exp_f32_e32 v83, v83
	v_exp_f32_e32 v8, v8
	v_exp_f32_e32 v9, v9
	v_fmamk_f32 v84, v84, 0x3e0293ee, v5
	v_fmamk_f32 v85, v85, 0x3e0293ee, v5
	v_fmamk_f32 v10, v102, 0x3e0293ee, v5
	v_fmamk_f32 v11, v103, 0x3e0293ee, v5
	v_exp_f32_e32 v84, v84
	v_exp_f32_e32 v85, v85
	v_exp_f32_e32 v10, v10
	v_exp_f32_e32 v11, v11
	v_fmamk_f32 v86, v86, 0x3e0293ee, v5
	v_fmamk_f32 v87, v87, 0x3e0293ee, v5
	v_pk_add_f32 v[102:103], v[6:7], 0 op_sel_hi:[1,0]
	v_fmamk_f32 v12, v104, 0x3e0293ee, v5
	v_fmamk_f32 v13, v105, 0x3e0293ee, v5
	v_exp_f32_e32 v86, v86
	v_exp_f32_e32 v87, v87
	v_pk_add_f32 v[102:103], v[82:83], v[102:103]
	v_exp_f32_e32 v12, v12
	v_exp_f32_e32 v13, v13
	v_fmamk_f32 v88, v88, 0x3e0293ee, v5
	v_fmamk_f32 v89, v89, 0x3e0293ee, v5
	v_pk_add_f32 v[102:103], v[8:9], v[102:103]
	v_fmamk_f32 v14, v106, 0x3e0293ee, v5
	v_fmamk_f32 v15, v107, 0x3e0293ee, v5
	v_exp_f32_e32 v88, v88
	v_exp_f32_e32 v89, v89
	v_pk_add_f32 v[102:103], v[84:85], v[102:103]
	v_exp_f32_e32 v14, v14
	v_exp_f32_e32 v15, v15
	v_fmamk_f32 v90, v90, 0x3e0293ee, v5
	v_fmamk_f32 v91, v91, 0x3e0293ee, v5
	v_pk_add_f32 v[102:103], v[10:11], v[102:103]
	v_fmamk_f32 v16, v108, 0x3e0293ee, v5
	v_fmamk_f32 v17, v109, 0x3e0293ee, v5
	v_exp_f32_e32 v90, v90
	v_exp_f32_e32 v91, v91
	v_pk_add_f32 v[102:103], v[86:87], v[102:103]
	v_exp_f32_e32 v16, v16
	v_exp_f32_e32 v17, v17
	v_fmamk_f32 v92, v92, 0x3e0293ee, v5
	v_fmamk_f32 v93, v93, 0x3e0293ee, v5
	v_pk_add_f32 v[102:103], v[12:13], v[102:103]
	v_fmamk_f32 v98, v110, 0x3e0293ee, v5
	v_fmamk_f32 v99, v111, 0x3e0293ee, v5
	v_exp_f32_e32 v92, v92
	v_exp_f32_e32 v93, v93
	v_pk_add_f32 v[102:103], v[88:89], v[102:103]
	v_exp_f32_e32 v98, v98
	v_exp_f32_e32 v99, v99
	v_fmamk_f32 v94, v94, 0x3e0293ee, v5
	v_fmamk_f32 v95, v95, 0x3e0293ee, v5
	v_pk_add_f32 v[102:103], v[14:15], v[102:103]
	v_fmamk_f32 v100, v112, 0x3e0293ee, v5
	v_fmamk_f32 v101, v113, 0x3e0293ee, v5
	v_exp_f32_e32 v94, v94
	v_exp_f32_e32 v95, v95
	v_pk_add_f32 v[102:103], v[90:91], v[102:103]
	v_exp_f32_e32 v100, v100
	v_exp_f32_e32 v101, v101
	v_fmamk_f32 v96, v96, 0x3e0293ee, v5
	v_fmac_f32_e32 v5, 0x3e0293ee, v97
	v_pk_add_f32 v[102:103], v[16:17], v[102:103]
	v_exp_f32_e32 v96, v96
	v_exp_f32_e32 v97, v5
	v_pk_add_f32 v[102:103], v[92:93], v[102:103]
	v_cvt_pk_f16_f32 v4, v6, v7
	v_pk_add_f32 v[102:103], v[98:99], v[102:103]
	v_cvt_pk_f16_f32 v5, v8, v9
	v_pk_add_f32 v[102:103], v[94:95], v[102:103]
	v_cvt_pk_f16_f32 v6, v10, v11
	v_pk_add_f32 v[102:103], v[100:101], v[102:103]
	v_cvt_pk_f16_f32 v7, v12, v13
	v_pk_add_f32 v[102:103], v[96:97], v[102:103]
	v_cvt_pk_f16_f32 v8, v14, v15
	v_pk_add_f32 v[102:103], v[102:103], v[102:103] op_sel:[0,1] op_sel_hi:[1,0]
	v_cvt_pk_f16_f32 v9, v16, v17
	v_mov_b32_e32 v103, v102
	v_cvt_pk_f16_f32 v10, v98, v99
	v_cvt_pk_f16_f32 v11, v100, v101
	v_permlane32_swap_b32_e32 v102, v103
	v_cvt_pk_f16_f32 v12, v82, v83
	v_add_f32_e32 v103, v102, v103
	v_cvt_pk_f16_f32 v13, v84, v85
	v_fma_f32 v183, v183, v188, v103
	v_cvt_pk_f16_f32 v14, v86, v87
	v_cvt_pk_f16_f32 v15, v88, v89
	v_cvt_pk_f16_f32 v82, v90, v91
	v_cvt_pk_f16_f32 v83, v92, v93
	v_cvt_pk_f16_f32 v84, v94, v95
	v_cvt_pk_f16_f32 v85, v96, v97
	v_permlane32_swap_b32_e32 v4, v6
	v_permlane32_swap_b32_e32 v5, v7
	v_permlane32_swap_b32_e32 v8, v10
	v_permlane32_swap_b32_e32 v9, v11
	v_permlane32_swap_b32_e32 v12, v14
	v_permlane32_swap_b32_e32 v13, v15
	v_permlane32_swap_b32_e32 v82, v84
	v_permlane32_swap_b32_e32 v83, v85
	v_add_u32_e32 v2, v180, v2
	ds_read_b64_tr_b16 v[86:87], v2 offset:0
	ds_read_b64_tr_b16 v[88:89], v2 offset:0x800
	ds_read_b64_tr_b16 v[90:91], v2 offset:0x1000
	ds_read_b64_tr_b16 v[92:93], v2 offset:0x1800
	ds_read_b64_tr_b16 v[94:95], v2 offset:0x2000
	ds_read_b64_tr_b16 v[96:97], v2 offset:0x2800
	ds_read_b64_tr_b16 v[98:99], v2 offset:0x3000
	ds_read_b64_tr_b16 v[100:101], v2 offset:0x3800
	ds_read_b64_tr_b16 v[102:103], v2 offset:0x200
	ds_read_b64_tr_b16 v[104:105], v2 offset:0xa00
	ds_read_b64_tr_b16 v[106:107], v2 offset:0x1200
	ds_read_b64_tr_b16 v[108:109], v2 offset:0x1a00
	ds_read_b64_tr_b16 v[110:111], v2 offset:0x2200
	ds_read_b64_tr_b16 v[112:113], v2 offset:0x2a00
	ds_read_b64_tr_b16 v[184:185], v2 offset:0x3200
	ds_read_b64_tr_b16 v[186:187], v2 offset:0x3a00
	s_waitcnt lgkmcnt(8)
	s_nop 0
	v_mfma_f32_32x32x16_f16 v[66:81], v[4:7], v[86:89], v[66:81]
	v_mfma_f32_32x32x16_f16 v[66:81], v[8:11], v[90:93], v[66:81]
	v_mfma_f32_32x32x16_f16 v[66:81], v[12:15], v[94:97], v[66:81]
	v_mfma_f32_32x32x16_f16 v[66:81], v[82:85], v[98:101], v[66:81]
	ds_read_b64_tr_b16 v[86:87], v2 offset:0x400
	ds_read_b64_tr_b16 v[88:89], v2 offset:0xc00
	ds_read_b64_tr_b16 v[90:91], v2 offset:0x1400
	ds_read_b64_tr_b16 v[92:93], v2 offset:0x1c00
	ds_read_b64_tr_b16 v[94:95], v2 offset:0x2400
	ds_read_b64_tr_b16 v[96:97], v2 offset:0x2c00
	ds_read_b64_tr_b16 v[98:99], v2 offset:0x3400
	ds_read_b64_tr_b16 v[100:101], v2 offset:0x3c00
	s_waitcnt lgkmcnt(8)
	v_mfma_f32_32x32x16_f16 v[50:65], v[4:7], v[102:105], v[50:65]
	v_mfma_f32_32x32x16_f16 v[50:65], v[8:11], v[106:109], v[50:65]
	v_mfma_f32_32x32x16_f16 v[50:65], v[12:15], v[110:113], v[50:65]
	v_mfma_f32_32x32x16_f16 v[50:65], v[82:85], v[184:187], v[50:65]
	ds_read_b64_tr_b16 v[102:103], v2 offset:0x600
	ds_read_b64_tr_b16 v[104:105], v2 offset:0xe00
	ds_read_b64_tr_b16 v[106:107], v2 offset:0x1600
	ds_read_b64_tr_b16 v[108:109], v2 offset:0x1e00
	ds_read_b64_tr_b16 v[110:111], v2 offset:0x2600
	ds_read_b64_tr_b16 v[112:113], v2 offset:0x2e00
	ds_read_b64_tr_b16 v[184:185], v2 offset:0x3600
	ds_read_b64_tr_b16 v[186:187], v2 offset:0x3e00
	s_waitcnt lgkmcnt(8)
	v_mfma_f32_32x32x16_f16 v[34:49], v[4:7], v[86:89], v[34:49]
	v_mfma_f32_32x32x16_f16 v[34:49], v[8:11], v[90:93], v[34:49]
	v_mfma_f32_32x32x16_f16 v[34:49], v[12:15], v[94:97], v[34:49]
	v_mfma_f32_32x32x16_f16 v[34:49], v[82:85], v[98:101], v[34:49]
	s_waitcnt lgkmcnt(0)
	v_mfma_f32_32x32x16_f16 v[18:33], v[4:7], v[102:105], v[18:33]
	v_mfma_f32_32x32x16_f16 v[18:33], v[8:11], v[106:109], v[18:33]
	v_mfma_f32_32x32x16_f16 v[18:33], v[12:15], v[110:113], v[18:33]
	v_mfma_f32_32x32x16_f16 v[18:33], v[82:85], v[184:187], v[18:33]
